# adds: on the 256-WG grid the next unit of P2/P5 is derived as (same panel, column tile + 4) instead of the general division-emulating decode; (exchange-protocol change of the previous version not incl
# speedup vs baseline: 1.0004x; 1.0004x over previous
.LBB0_242:
	s_add_i32 s86, s86, 1
	s_mul_i32 s0, s86, s89
	s_mul_hi_u32 s4, s86, s33
	s_add_i32 s4, s4, s0
	s_mul_i32 s0, s86, s33
	s_add_u32 s74, s0, s2
	s_addc_u32 s75, s4, s3
	v_cmp_gt_i64_e32 vcc, s[74:75], v[156:157]
	v_cmp_lt_i64_e64 s[4:5], s[74:75], v[154:155]
	s_cbranch_vccnz .LBB0_244
	s_and_b64 vcc, exec, s[62:63]
	s_cbranch_vccnz .Ldec2_general
	s_add_i32 s46, s78, 4
	s_mov_b32 s72, s6
	s_branch .LBB0_244
.Ldec2_general:
	s_ashr_i32 s0, s74, 31
	s_lshr_b32 s0, s0, 29
	s_add_i32 s0, s74, s0
	s_ashr_i32 s7, s0, 3
	s_and_b32 s0, s0, -8
	s_sub_i32 s0, s74, s0
	s_cmp_lt_i32 s0, 0
	s_movk_i32 s46, 0x51
	s_cselect_b32 s46, s46, 0x50
	s_mul_i32 s0, s0, s46
	s_add_i32 s0, s0, s7
	s_mul_hi_i32 s7, s0, 0x66666667
	s_lshr_b32 s46, s7, 31
	s_ashr_i32 s7, s7, 5
	s_add_i32 s7, s7, s46
	s_lshl_b32 s47, s7, 3
	s_sub_i32 s46, 64, s47
	s_min_i32 s72, s46, 8
	s_abs_i32 s46, s72
	v_cvt_f32_u32_e32 v2, s46
	s_sub_i32 s74, 0, s46
	s_mulk_i32 s7, 0x50
	s_sub_i32 s0, s0, s7
	v_rcp_iflag_f32_e32 v2, v2
	s_abs_i32 s7, s0
	s_xor_b32 s73, s0, s72
	s_ashr_i32 s73, s73, 31
	v_mul_f32_e32 v2, 0x4f7ffffe, v2
	v_cvt_u32_f32_e32 v2, v2
	s_nop 0
	v_readfirstlane_b32 s75, v2
	s_mul_i32 s74, s74, s75
	s_mul_hi_u32 s74, s75, s74
	s_add_i32 s75, s75, s74
	s_mul_hi_u32 s74, s7, s75
	s_mul_i32 s75, s74, s46
	s_sub_i32 s7, s7, s75
	s_add_i32 s76, s74, 1
	s_sub_i32 s75, s7, s46
	s_cmp_ge_u32 s7, s46
	s_cselect_b32 s74, s76, s74
	s_cselect_b32 s7, s75, s7
	s_add_i32 s75, s74, 1
	s_cmp_ge_u32 s7, s46
	s_cselect_b32 s7, s75, s74
	s_xor_b32 s7, s7, s73
	s_sub_i32 s46, s7, s73
	s_mul_i32 s7, s46, s72
	s_sub_i32 s0, s0, s7
	s_add_i32 s72, s47, s0

.LBB0_765:
	s_add_i32 s47, s47, 1
	s_mul_i32 s0, s47, s50
	s_mul_hi_u32 s6, s47, s33
	s_add_i32 s6, s6, s0
	s_mul_i32 s0, s47, s33
	s_add_u32 s20, s0, s2
	s_addc_u32 s21, s6, s3
	v_cmp_gt_i64_e32 vcc, s[20:21], v[144:145]
	v_cmp_lt_i64_e64 s[6:7], s[20:21], v[142:143]
	s_cbranch_vccnz .LBB0_767
	s_and_b64 vcc, exec, s[62:63]
	s_cbranch_vccnz .Ldec5_general
	s_add_i32 s16, s28, 4
	s_mov_b32 s18, s36
	s_branch .LBB0_767
.Ldec5_general:
	s_ashr_i32 s0, s20, 31
	s_lshr_b32 s0, s0, 29
	s_add_i32 s0, s20, s0
	s_ashr_i32 s16, s0, 3
	s_and_b32 s0, s0, -8
	s_sub_i32 s0, s20, s0
	s_cmp_lt_i32 s0, 0
	s_cselect_b32 s17, s44, 0xb0
	s_mul_i32 s0, s0, s17
	s_add_i32 s0, s0, s16
	s_mul_hi_i32 s16, s0, 0x2e8ba2e9
	s_lshr_b32 s17, s16, 31
	s_ashr_i32 s16, s16, 5
	s_add_i32 s16, s16, s17
	s_lshl_b32 s17, s16, 3
	s_sub_i32 s18, 64, s17
	s_min_i32 s18, s18, 8
	s_abs_i32 s19, s18
	v_cvt_f32_u32_e32 v2, s19
	s_sub_i32 s21, 0, s19
	s_mulk_i32 s16, 0xb0
	s_sub_i32 s0, s0, s16
	v_rcp_iflag_f32_e32 v2, v2
	s_abs_i32 s16, s0
	s_xor_b32 s20, s0, s18
	s_ashr_i32 s20, s20, 31
	v_mul_f32_e32 v2, 0x4f7ffffe, v2
	v_cvt_u32_f32_e32 v2, v2
	s_nop 0
	v_readfirstlane_b32 s26, v2
	s_mul_i32 s21, s21, s26
	s_mul_hi_u32 s21, s26, s21
	s_add_i32 s26, s26, s21
	s_mul_hi_u32 s21, s16, s26
	s_mul_i32 s26, s21, s19
	s_sub_i32 s16, s16, s26
	s_add_i32 s27, s21, 1
	s_sub_i32 s26, s16, s19
	s_cmp_ge_u32 s16, s19
	s_cselect_b32 s21, s27, s21
	s_cselect_b32 s16, s26, s16
	s_add_i32 s26, s21, 1
	s_cmp_ge_u32 s16, s19
	s_cselect_b32 s16, s26, s21
	s_xor_b32 s16, s16, s20
	s_sub_i32 s16, s16, s20
	s_mul_i32 s18, s16, s18
	s_sub_i32 s0, s0, s18
	s_add_i32 s18, s17, s0
